# G1 first-K-tile-after-epilogue skips vmcnt waits; sparse attention loop LDS fragment prefetch; G1 start skew
# speedup vs baseline: 1.0167x; 1.0167x over previous
.LBB0_205:
	s_bfe_u32 s4, s2, 0x30003
	s_cmp_eq_u32 s4, 0
	s_cbranch_scc1 .Lskew_done_g1
.Lskew_loop_g1:
	s_sleep 48
	s_sub_u32 s4, s4, 1
	s_cmp_lg_u32 s4, 0
	s_cbranch_scc1 .Lskew_loop_g1

.LBB0_212:
	s_ashr_i32 s65, s64, 31
	s_lshl_b64 s[68:69], s[64:65], 19
	s_cmp_eq_u32 s29, 0
	s_cselect_b32 s18, s48, 0
	s_cselect_b32 s15, s49, 0
	s_cselect_b32 s45, s61, 0
	s_cselect_b32 s65, s63, 0
	s_add_u32 s68, s18, s68
	s_addc_u32 s69, s15, s69
	s_and_b64 s[70:71], s[74:75], exec
	s_cselect_b32 s15, s69, s5
	s_cselect_b32 s18, s68, s4
	s_ashr_i32 s67, s66, 31
	s_lshl_b64 s[70:71], s[66:67], 19
	s_add_u32 s70, s45, s70
	s_addc_u32 s71, s65, s71
	s_and_b64 s[74:75], s[74:75], exec
	s_cselect_b32 s45, s71, s73
	s_cselect_b32 s65, s70, s72
	s_add_u32 s4, s4, 0x40080
	s_addc_u32 s5, s5, 0
	s_add_u32 s67, s72, 0x100
	v_mov_b32_e32 v0, 0
	s_addc_u32 s76, s73, 0
	s_mov_b32 s77, -2
	v_mov_b32_e32 v1, v0
	v_mov_b32_e32 v2, v0
	v_mov_b32_e32 v3, v0
	v_mov_b32_e32 v4, v0
	v_mov_b32_e32 v5, v0
	v_mov_b32_e32 v6, v0
	v_mov_b32_e32 v7, v0
	v_mov_b32_e32 v16, v0
	v_mov_b32_e32 v17, v0
	v_mov_b32_e32 v18, v0
	v_mov_b32_e32 v19, v0
	v_mov_b32_e32 v20, v0
	v_mov_b32_e32 v21, v0
	v_mov_b32_e32 v22, v0
	v_mov_b32_e32 v23, v0
	v_mov_b32_e32 v32, v0
	v_mov_b32_e32 v33, v0
	v_mov_b32_e32 v34, v0
	v_mov_b32_e32 v35, v0
	v_mov_b32_e32 v36, v0
	v_mov_b32_e32 v37, v0
	v_mov_b32_e32 v38, v0
	v_mov_b32_e32 v39, v0
	v_mov_b32_e32 v48, v0
	v_mov_b32_e32 v49, v0
	v_mov_b32_e32 v50, v0
	v_mov_b32_e32 v51, v0
	v_mov_b32_e32 v52, v0
	v_mov_b32_e32 v53, v0
	v_mov_b32_e32 v54, v0
	v_mov_b32_e32 v55, v0
	v_mov_b32_e32 v8, v0
	v_mov_b32_e32 v9, v0
	v_mov_b32_e32 v10, v0
	v_mov_b32_e32 v11, v0
	v_mov_b32_e32 v12, v0
	v_mov_b32_e32 v13, v0
	v_mov_b32_e32 v14, v0
	v_mov_b32_e32 v15, v0
	v_mov_b32_e32 v24, v0
	v_mov_b32_e32 v25, v0
	v_mov_b32_e32 v26, v0
	v_mov_b32_e32 v27, v0
	v_mov_b32_e32 v28, v0
	v_mov_b32_e32 v29, v0
	v_mov_b32_e32 v30, v0
	v_mov_b32_e32 v31, v0
	v_mov_b32_e32 v40, v0
	v_mov_b32_e32 v41, v0
	v_mov_b32_e32 v42, v0
	v_mov_b32_e32 v43, v0
	v_mov_b32_e32 v44, v0
	v_mov_b32_e32 v45, v0
	v_mov_b32_e32 v46, v0
	v_mov_b32_e32 v47, v0
	v_mov_b32_e32 v56, v0
	v_mov_b32_e32 v57, v0
	v_mov_b32_e32 v58, v0
	v_mov_b32_e32 v59, v0
	v_mov_b32_e32 v60, v0
	v_mov_b32_e32 v61, v0
	v_mov_b32_e32 v62, v0
	v_mov_b32_e32 v63, v0
	v_mov_b32_e32 v64, v0
	v_mov_b32_e32 v65, v0
	v_mov_b32_e32 v66, v0
	v_mov_b32_e32 v67, v0
	v_mov_b32_e32 v68, v0
	v_mov_b32_e32 v69, v0
	v_mov_b32_e32 v70, v0
	v_mov_b32_e32 v71, v0
	v_mov_b32_e32 v80, v0
	v_mov_b32_e32 v81, v0
	v_mov_b32_e32 v82, v0
	v_mov_b32_e32 v83, v0
	v_mov_b32_e32 v84, v0
	v_mov_b32_e32 v85, v0
	v_mov_b32_e32 v86, v0
	v_mov_b32_e32 v87, v0
	v_mov_b32_e32 v96, v0
	v_mov_b32_e32 v97, v0
	v_mov_b32_e32 v98, v0
	v_mov_b32_e32 v99, v0
	v_mov_b32_e32 v100, v0
	v_mov_b32_e32 v101, v0
	v_mov_b32_e32 v102, v0
	v_mov_b32_e32 v103, v0
	v_mov_b32_e32 v112, v0
	v_mov_b32_e32 v113, v0
	v_mov_b32_e32 v114, v0
	v_mov_b32_e32 v115, v0
	v_mov_b32_e32 v116, v0
	v_mov_b32_e32 v117, v0
	v_mov_b32_e32 v118, v0
	v_mov_b32_e32 v119, v0
	v_mov_b32_e32 v72, v0
	v_mov_b32_e32 v73, v0
	v_mov_b32_e32 v74, v0
	v_mov_b32_e32 v75, v0
	v_mov_b32_e32 v76, v0
	v_mov_b32_e32 v77, v0
	v_mov_b32_e32 v78, v0
	v_mov_b32_e32 v79, v0
	v_mov_b32_e32 v88, v0
	v_mov_b32_e32 v89, v0
	v_mov_b32_e32 v90, v0
	v_mov_b32_e32 v91, v0
	v_mov_b32_e32 v92, v0
	v_mov_b32_e32 v93, v0
	v_mov_b32_e32 v94, v0
	v_mov_b32_e32 v95, v0
	v_mov_b32_e32 v104, v0
	v_mov_b32_e32 v105, v0
	v_mov_b32_e32 v106, v0
	v_mov_b32_e32 v107, v0
	v_mov_b32_e32 v108, v0
	v_mov_b32_e32 v109, v0
	v_mov_b32_e32 v110, v0
	v_mov_b32_e32 v111, v0
	v_mov_b32_e32 v120, v0
	v_mov_b32_e32 v121, v0
	v_mov_b32_e32 v122, v0
	v_mov_b32_e32 v123, v0
	v_mov_b32_e32 v124, v0
	v_mov_b32_e32 v125, v0
	v_mov_b32_e32 v126, v0
	v_mov_b32_e32 v127, v0
	s_cmp_lg_u32 s80, 0
	s_cselect_b32 s98, 1, 0
.LBB0_213:
	ds_read_b128 v[128:131], v175
	ds_read_b128 v[132:135], v175 offset:1024
	ds_read_b128 v[150:153], v175 offset:2048
	ds_read_b128 v[154:157], v175 offset:3072
	ds_read_b128 v[186:189], v177
	ds_read_b128 v[190:193], v177 offset:1024
	ds_read_b128 v[194:197], v177 offset:2048
	ds_read_b128 v[198:201], v177 offset:3072
	s_add_u32 s72, s4, 0xfffc0080
	s_addc_u32 s73, s5, -1
	s_cmp_eq_u32 s77, 12
	s_cselect_b32 s75, s15, s73
	s_cselect_b32 s74, s18, s72
	s_cselect_b32 s73, s45, s76
	s_cselect_b32 s72, s65, s67
	v_lshl_add_u64 v[158:159], s[4:5], 0, v[146:147]
	s_add_i32 m0, s17, 0xc000
	ds_read_b128 v[202:205], v179
	ds_read_b128 v[206:209], v179 offset:1024
	ds_read_b128 v[210:213], v179 offset:2048
	ds_read_b128 v[214:217], v179 offset:3072
	ds_read_b128 v[218:221], v179 offset:4096
	ds_read_b128 v[222:225], v179 offset:5120
	ds_read_b128 v[230:233], v179 offset:6144
	ds_read_b128 v[234:237], v179 offset:7168
	global_load_lds_dwordx4 v[158:159], off
	v_lshl_add_u64 v[158:159], s[4:5], 0, v[148:149]
	s_add_i32 m0, s17, 0xe000
	s_nop 0
	global_load_lds_dwordx4 v[158:159], off
	s_cmp_eq_u32 s98, 1
	s_cbranch_scc1 .Lg1_skw1
	s_waitcnt vmcnt(8)
.Lg1_skw1:
	s_waitcnt lgkmcnt(0)
	s_barrier
	s_setprio 1
	s_waitcnt lgkmcnt(0)
	v_mfma_f32_16x16x32_bf16 v[124:127], v[128:131], v[202:205], v[124:127]
	v_mfma_f32_16x16x32_bf16 v[120:123], v[150:153], v[202:205], v[120:123]
	v_mfma_f32_16x16x32_bf16 v[108:111], v[128:131], v[210:213], v[108:111]
	v_mfma_f32_16x16x32_bf16 v[104:107], v[150:153], v[210:213], v[104:107]
	v_mfma_f32_16x16x32_bf16 v[92:95], v[128:131], v[218:221], v[92:95]
	v_mfma_f32_16x16x32_bf16 v[88:91], v[150:153], v[218:221], v[88:91]
	v_mfma_f32_16x16x32_bf16 v[76:79], v[128:131], v[230:233], v[76:79]
	v_mfma_f32_16x16x32_bf16 v[72:75], v[150:153], v[230:233], v[72:75]
	v_mfma_f32_16x16x32_bf16 v[124:127], v[132:135], v[206:209], v[124:127]
	v_mfma_f32_16x16x32_bf16 v[120:123], v[154:157], v[206:209], v[120:123]
	v_mfma_f32_16x16x32_bf16 v[108:111], v[132:135], v[214:217], v[108:111]
	v_mfma_f32_16x16x32_bf16 v[104:107], v[154:157], v[214:217], v[104:107]
	v_mfma_f32_16x16x32_bf16 v[92:95], v[132:135], v[222:225], v[92:95]
	v_mfma_f32_16x16x32_bf16 v[88:91], v[154:157], v[222:225], v[88:91]
	v_mfma_f32_16x16x32_bf16 v[76:79], v[132:135], v[234:237], v[76:79]
	v_mfma_f32_16x16x32_bf16 v[72:75], v[154:157], v[234:237], v[72:75]
	s_setprio 0
	s_setprio 1
	v_mfma_f32_16x16x32_bf16 v[116:119], v[186:189], v[202:205], v[116:119]
	v_mfma_f32_16x16x32_bf16 v[112:115], v[194:197], v[202:205], v[112:115]
	v_mfma_f32_16x16x32_bf16 v[100:103], v[186:189], v[210:213], v[100:103]
	v_mfma_f32_16x16x32_bf16 v[96:99], v[194:197], v[210:213], v[96:99]
	v_mfma_f32_16x16x32_bf16 v[84:87], v[186:189], v[218:221], v[84:87]
	v_mfma_f32_16x16x32_bf16 v[80:83], v[194:197], v[218:221], v[80:83]
	v_mfma_f32_16x16x32_bf16 v[68:71], v[186:189], v[230:233], v[68:71]
	v_mfma_f32_16x16x32_bf16 v[64:67], v[194:197], v[230:233], v[64:67]
	v_mfma_f32_16x16x32_bf16 v[116:119], v[190:193], v[206:209], v[116:119]
	v_mfma_f32_16x16x32_bf16 v[112:115], v[198:201], v[206:209], v[112:115]
	v_mfma_f32_16x16x32_bf16 v[100:103], v[190:193], v[214:217], v[100:103]
	v_mfma_f32_16x16x32_bf16 v[96:99], v[198:201], v[214:217], v[96:99]
	v_mfma_f32_16x16x32_bf16 v[84:87], v[190:193], v[222:225], v[84:87]
	v_mfma_f32_16x16x32_bf16 v[80:83], v[198:201], v[222:225], v[80:83]
	v_mfma_f32_16x16x32_bf16 v[68:71], v[190:193], v[234:237], v[68:71]
	v_mfma_f32_16x16x32_bf16 v[64:67], v[198:201], v[234:237], v[64:67]
	s_setprio 0
	s_barrier
	s_add_i32 vcc_lo, s30, s53
	v_lshl_add_u64 v[158:159], s[72:73], 0, v[138:139]
	s_mov_b32 m0, vcc_lo
	ds_read_b128 v[202:205], v179 offset:16384
	ds_read_b128 v[206:209], v179 offset:17408
	ds_read_b128 v[210:213], v179 offset:18432
	ds_read_b128 v[214:217], v179 offset:19456
	ds_read_b128 v[218:221], v179 offset:20480
	ds_read_b128 v[222:225], v179 offset:21504
	ds_read_b128 v[230:233], v179 offset:22528
	ds_read_b128 v[234:237], v179 offset:23552
	global_load_lds_dwordx4 v[158:159], off
	s_add_i32 m0, vcc_lo, 0x2000
	s_add_u32 vcc_lo, s72, 0x40000
	v_lshl_add_u64 v[180:181], s[72:73], 0, v[142:143]
	s_addc_u32 vcc_hi, s73, 0
	s_add_i32 s79, s31, s53
	global_load_lds_dwordx4 v[180:181], off
	v_lshl_add_u64 v[226:227], vcc, 0, v[138:139]
	s_mov_b32 m0, s79
	v_lshl_add_u64 v[238:239], s[74:75], 0, v[140:141]
	global_load_lds_dwordx4 v[226:227], off
	v_lshl_add_u64 v[226:227], vcc, 0, v[142:143]
	s_add_i32 m0, s79, 0x2000
	s_nop 0
	global_load_lds_dwordx4 v[226:227], off
	v_lshl_add_u64 v[226:227], s[74:75], 0, v[136:137]
	s_mov_b32 m0, s17
	s_nop 0
	global_load_lds_dwordx4 v[226:227], off
	s_mov_b32 m0, s81
	s_nop 0
	global_load_lds_dwordx4 v[238:239], off
	s_cmp_eq_u32 s98, 1
	s_cbranch_scc1 .Lg1_skw2
	s_waitcnt vmcnt(8)
.Lg1_skw2:
	s_mov_b32 s98, 0
	s_waitcnt lgkmcnt(0)
	s_barrier
	s_setprio 1
	s_waitcnt lgkmcnt(0)
	v_mfma_f32_16x16x32_bf16 v[60:63], v[128:131], v[202:205], v[60:63]
	v_mfma_f32_16x16x32_bf16 v[56:59], v[150:153], v[202:205], v[56:59]
	v_mfma_f32_16x16x32_bf16 v[44:47], v[128:131], v[210:213], v[44:47]
	v_mfma_f32_16x16x32_bf16 v[40:43], v[150:153], v[210:213], v[40:43]
	v_mfma_f32_16x16x32_bf16 v[28:31], v[128:131], v[218:221], v[28:31]
	v_mfma_f32_16x16x32_bf16 v[24:27], v[150:153], v[218:221], v[24:27]
	v_mfma_f32_16x16x32_bf16 v[12:15], v[128:131], v[230:233], v[12:15]
	v_mfma_f32_16x16x32_bf16 v[8:11], v[150:153], v[230:233], v[8:11]
	v_mfma_f32_16x16x32_bf16 v[60:63], v[132:135], v[206:209], v[60:63]
	v_mfma_f32_16x16x32_bf16 v[56:59], v[154:157], v[206:209], v[56:59]
	v_mfma_f32_16x16x32_bf16 v[44:47], v[132:135], v[214:217], v[44:47]
	v_mfma_f32_16x16x32_bf16 v[40:43], v[154:157], v[214:217], v[40:43]
	v_mfma_f32_16x16x32_bf16 v[28:31], v[132:135], v[222:225], v[28:31]
	v_mfma_f32_16x16x32_bf16 v[24:27], v[154:157], v[222:225], v[24:27]
	v_mfma_f32_16x16x32_bf16 v[12:15], v[132:135], v[234:237], v[12:15]
	v_mfma_f32_16x16x32_bf16 v[8:11], v[154:157], v[234:237], v[8:11]
	s_setprio 0
	s_setprio 1
	v_mfma_f32_16x16x32_bf16 v[52:55], v[186:189], v[202:205], v[52:55]
	v_mfma_f32_16x16x32_bf16 v[48:51], v[194:197], v[202:205], v[48:51]
	v_mfma_f32_16x16x32_bf16 v[36:39], v[186:189], v[210:213], v[36:39]
	v_mfma_f32_16x16x32_bf16 v[32:35], v[194:197], v[210:213], v[32:35]
	v_mfma_f32_16x16x32_bf16 v[20:23], v[186:189], v[218:221], v[20:23]
	v_mfma_f32_16x16x32_bf16 v[16:19], v[194:197], v[218:221], v[16:19]
	v_mfma_f32_16x16x32_bf16 v[4:7], v[186:189], v[230:233], v[4:7]
	v_mfma_f32_16x16x32_bf16 v[0:3], v[194:197], v[230:233], v[0:3]
	v_mfma_f32_16x16x32_bf16 v[52:55], v[190:193], v[206:209], v[52:55]
	v_mfma_f32_16x16x32_bf16 v[48:51], v[198:201], v[206:209], v[48:51]
	v_mfma_f32_16x16x32_bf16 v[36:39], v[190:193], v[214:217], v[36:39]
	v_mfma_f32_16x16x32_bf16 v[32:35], v[198:201], v[214:217], v[32:35]
	v_mfma_f32_16x16x32_bf16 v[20:23], v[190:193], v[222:225], v[20:23]
	v_mfma_f32_16x16x32_bf16 v[16:19], v[198:201], v[222:225], v[16:19]
	v_mfma_f32_16x16x32_bf16 v[4:7], v[190:193], v[234:237], v[4:7]
	v_mfma_f32_16x16x32_bf16 v[0:3], v[198:201], v[234:237], v[0:3]
	s_setprio 0
	s_barrier
	s_add_i32 s79, 0, 0x18000
	v_add_u32_e32 v144, s79, v161
	s_add_i32 vcc_lo, 0, 0x1c000
	ds_read_b128 v[128:131], v144
	ds_read_b128 v[132:135], v144 offset:1024
	ds_read_b128 v[150:153], v144 offset:2048
	ds_read_b128 v[154:157], v144 offset:3072
	v_add_u32_e32 v144, vcc_lo, v161
	ds_read_b128 v[186:189], v144
	ds_read_b128 v[190:193], v144 offset:1024
	ds_read_b128 v[194:197], v144 offset:2048
	ds_read_b128 v[198:201], v144 offset:3072
	s_add_u32 s74, s74, 0x40000
	s_addc_u32 s75, s75, 0
	s_mov_b32 m0, s82
	v_lshl_add_u64 v[240:241], s[74:75], 0, v[136:137]
	ds_read_b128 v[202:205], v179 offset:32768
	ds_read_b128 v[206:209], v179 offset:33792
	ds_read_b128 v[210:213], v179 offset:34816
	ds_read_b128 v[214:217], v179 offset:35840
	ds_read_b128 v[218:221], v179 offset:36864
	ds_read_b128 v[222:225], v179 offset:37888
	ds_read_b128 v[230:233], v179 offset:38912
	ds_read_b128 v[234:237], v179 offset:39936
	global_load_lds_dwordx4 v[240:241], off
	v_lshl_add_u64 v[240:241], s[74:75], 0, v[140:141]
	s_mov_b32 m0, s83
	s_nop 0
	global_load_lds_dwordx4 v[240:241], off
	s_waitcnt vmcnt(8)
	s_waitcnt lgkmcnt(0)
	s_barrier
	s_setprio 1
	s_waitcnt lgkmcnt(0)
	v_mfma_f32_16x16x32_bf16 v[124:127], v[128:131], v[202:205], v[124:127]
	v_mfma_f32_16x16x32_bf16 v[120:123], v[150:153], v[202:205], v[120:123]
	v_mfma_f32_16x16x32_bf16 v[108:111], v[128:131], v[210:213], v[108:111]
	v_mfma_f32_16x16x32_bf16 v[104:107], v[150:153], v[210:213], v[104:107]
	v_mfma_f32_16x16x32_bf16 v[92:95], v[128:131], v[218:221], v[92:95]
	v_mfma_f32_16x16x32_bf16 v[88:91], v[150:153], v[218:221], v[88:91]
	v_mfma_f32_16x16x32_bf16 v[76:79], v[128:131], v[230:233], v[76:79]
	v_mfma_f32_16x16x32_bf16 v[72:75], v[150:153], v[230:233], v[72:75]
	v_mfma_f32_16x16x32_bf16 v[124:127], v[132:135], v[206:209], v[124:127]
	v_mfma_f32_16x16x32_bf16 v[120:123], v[154:157], v[206:209], v[120:123]
	v_mfma_f32_16x16x32_bf16 v[108:111], v[132:135], v[214:217], v[108:111]
	v_mfma_f32_16x16x32_bf16 v[104:107], v[154:157], v[214:217], v[104:107]
	v_mfma_f32_16x16x32_bf16 v[92:95], v[132:135], v[222:225], v[92:95]
	v_mfma_f32_16x16x32_bf16 v[88:91], v[154:157], v[222:225], v[88:91]
	v_mfma_f32_16x16x32_bf16 v[76:79], v[132:135], v[234:237], v[76:79]
	v_mfma_f32_16x16x32_bf16 v[72:75], v[154:157], v[234:237], v[72:75]
	s_setprio 0
	s_setprio 1
	v_mfma_f32_16x16x32_bf16 v[116:119], v[186:189], v[202:205], v[116:119]
	v_mfma_f32_16x16x32_bf16 v[112:115], v[194:197], v[202:205], v[112:115]
	v_mfma_f32_16x16x32_bf16 v[100:103], v[186:189], v[210:213], v[100:103]
	v_mfma_f32_16x16x32_bf16 v[96:99], v[194:197], v[210:213], v[96:99]
	v_mfma_f32_16x16x32_bf16 v[84:87], v[186:189], v[218:221], v[84:87]
	v_mfma_f32_16x16x32_bf16 v[80:83], v[194:197], v[218:221], v[80:83]
	v_mfma_f32_16x16x32_bf16 v[68:71], v[186:189], v[230:233], v[68:71]
	v_mfma_f32_16x16x32_bf16 v[64:67], v[194:197], v[230:233], v[64:67]
	v_mfma_f32_16x16x32_bf16 v[116:119], v[190:193], v[206:209], v[116:119]
	v_mfma_f32_16x16x32_bf16 v[112:115], v[198:201], v[206:209], v[112:115]
	v_mfma_f32_16x16x32_bf16 v[100:103], v[190:193], v[214:217], v[100:103]
	v_mfma_f32_16x16x32_bf16 v[96:99], v[198:201], v[214:217], v[96:99]
	v_mfma_f32_16x16x32_bf16 v[84:87], v[190:193], v[222:225], v[84:87]
	v_mfma_f32_16x16x32_bf16 v[80:83], v[198:201], v[222:225], v[80:83]
	v_mfma_f32_16x16x32_bf16 v[68:71], v[190:193], v[234:237], v[68:71]
	v_mfma_f32_16x16x32_bf16 v[64:67], v[198:201], v[234:237], v[64:67]
	s_setprio 0
	s_barrier
	s_add_i32 s74, s79, s53
	v_lshl_add_u64 v[158:159], v[158:159], 0, s[24:25]
	s_mov_b32 m0, s74
	ds_read_b128 v[202:205], v179 offset:49152
	ds_read_b128 v[206:209], v179 offset:50176
	ds_read_b128 v[210:213], v179 offset:51200
	ds_read_b128 v[214:217], v179 offset:52224
	ds_read_b128 v[218:221], v179 offset:53248
	ds_read_b128 v[222:225], v179 offset:54272
	ds_read_b128 v[230:233], v179 offset:55296
	ds_read_b128 v[234:237], v179 offset:56320
	global_load_lds_dwordx4 v[158:159], off
	s_add_i32 m0, s74, 0x2000
	s_add_u32 s72, s72, 0x40080
	v_lshl_add_u64 v[158:159], v[180:181], 0, s[24:25]
	s_addc_u32 s73, s73, 0
	s_add_i32 s74, vcc_lo, s53
	global_load_lds_dwordx4 v[158:159], off
	v_lshl_add_u64 v[158:159], s[72:73], 0, v[138:139]
	s_mov_b32 m0, s74
	s_nop 0
	global_load_lds_dwordx4 v[158:159], off
	v_lshl_add_u64 v[158:159], s[72:73], 0, v[142:143]
	s_add_i32 m0, s74, 0x2000
	s_nop 0
	global_load_lds_dwordx4 v[158:159], off
	v_lshl_add_u64 v[158:159], v[226:227], 0, s[24:25]
	s_mov_b32 m0, s86
	s_nop 0
	global_load_lds_dwordx4 v[158:159], off
	v_lshl_add_u64 v[158:159], v[238:239], 0, s[24:25]
	s_mov_b32 m0, s87
	s_nop 0
	global_load_lds_dwordx4 v[158:159], off
	s_waitcnt vmcnt(8)
	s_waitcnt lgkmcnt(0)
	s_barrier
	s_setprio 1
	s_waitcnt lgkmcnt(0)
	v_mfma_f32_16x16x32_bf16 v[60:63], v[128:131], v[202:205], v[60:63]
	v_mfma_f32_16x16x32_bf16 v[56:59], v[150:153], v[202:205], v[56:59]
	v_mfma_f32_16x16x32_bf16 v[44:47], v[128:131], v[210:213], v[44:47]
	v_mfma_f32_16x16x32_bf16 v[40:43], v[150:153], v[210:213], v[40:43]
	v_mfma_f32_16x16x32_bf16 v[28:31], v[128:131], v[218:221], v[28:31]
	v_mfma_f32_16x16x32_bf16 v[24:27], v[150:153], v[218:221], v[24:27]
	v_mfma_f32_16x16x32_bf16 v[12:15], v[128:131], v[230:233], v[12:15]
	v_mfma_f32_16x16x32_bf16 v[8:11], v[150:153], v[230:233], v[8:11]
	v_mfma_f32_16x16x32_bf16 v[60:63], v[132:135], v[206:209], v[60:63]
	v_mfma_f32_16x16x32_bf16 v[56:59], v[154:157], v[206:209], v[56:59]
	v_mfma_f32_16x16x32_bf16 v[44:47], v[132:135], v[214:217], v[44:47]
	v_mfma_f32_16x16x32_bf16 v[40:43], v[154:157], v[214:217], v[40:43]
	v_mfma_f32_16x16x32_bf16 v[28:31], v[132:135], v[222:225], v[28:31]
	v_mfma_f32_16x16x32_bf16 v[24:27], v[154:157], v[222:225], v[24:27]
	v_mfma_f32_16x16x32_bf16 v[12:15], v[132:135], v[234:237], v[12:15]
	v_mfma_f32_16x16x32_bf16 v[8:11], v[154:157], v[234:237], v[8:11]
	s_setprio 0
	s_setprio 1
	v_mfma_f32_16x16x32_bf16 v[52:55], v[186:189], v[202:205], v[52:55]
	v_mfma_f32_16x16x32_bf16 v[48:51], v[194:197], v[202:205], v[48:51]
	v_mfma_f32_16x16x32_bf16 v[36:39], v[186:189], v[210:213], v[36:39]
	v_mfma_f32_16x16x32_bf16 v[32:35], v[194:197], v[210:213], v[32:35]
	v_mfma_f32_16x16x32_bf16 v[20:23], v[186:189], v[218:221], v[20:23]
	v_mfma_f32_16x16x32_bf16 v[16:19], v[194:197], v[218:221], v[16:19]
	v_mfma_f32_16x16x32_bf16 v[4:7], v[186:189], v[230:233], v[4:7]
	v_mfma_f32_16x16x32_bf16 v[0:3], v[194:197], v[230:233], v[0:3]
	v_mfma_f32_16x16x32_bf16 v[52:55], v[190:193], v[206:209], v[52:55]
	v_mfma_f32_16x16x32_bf16 v[48:51], v[198:201], v[206:209], v[48:51]
	v_mfma_f32_16x16x32_bf16 v[36:39], v[190:193], v[214:217], v[36:39]
	v_mfma_f32_16x16x32_bf16 v[32:35], v[198:201], v[214:217], v[32:35]
	v_mfma_f32_16x16x32_bf16 v[20:23], v[190:193], v[222:225], v[20:23]
	v_mfma_f32_16x16x32_bf16 v[16:19], v[198:201], v[222:225], v[16:19]
	v_mfma_f32_16x16x32_bf16 v[4:7], v[190:193], v[234:237], v[4:7]
	v_mfma_f32_16x16x32_bf16 v[0:3], v[198:201], v[234:237], v[0:3]
	s_setprio 0
	s_barrier
	s_add_i32 s77, s77, 2
	s_add_u32 s4, s4, 0x100
	s_addc_u32 s5, s5, 0
	s_add_u32 s67, s67, 0x100
	s_addc_u32 s76, s76, 0
	s_cmp_gt_u32 s77, 13
	s_cbranch_scc0 .LBB0_213
	s_and_b64 vcc, exec, s[34:35]
	s_cbranch_vccz .LBB0_216
	s_barrier

.LBB0_263:
	v_lshl_add_u64 v[158:159], v[128:129], 0, s[58:59]
	s_mov_b64 s[4:5], 0
	v_cvt_pk_bf16_f32 v128, v132, v133
	v_cvt_pk_bf16_f32 v129, v130, v131
	v_cvt_pk_bf16_f32 v130, v156, v157
	v_cvt_pk_bf16_f32 v131, v134, v135
	global_store_dwordx4 v[158:159], v[128:131], off offset:256 nt
	s_waitcnt vmcnt(16)
.LBB0_264:
	s_and_b64 vcc, exec, s[4:5]
	s_cbranch_vccz .LBB0_266
	v_pk_mul_f32 v[128:129], v[126:127], s[60:61] op_sel_hi:[1,0]
	v_pk_mul_f32 v[132:133], v[124:125], s[60:61] op_sel_hi:[1,0]
	v_exp_f32_e32 v128, v128
	v_exp_f32_e32 v132, v132
	v_exp_f32_e32 v133, v133
	v_exp_f32_e32 v129, v129
	v_pk_mul_f32 v[156:157], v[120:121], s[60:61] op_sel_hi:[1,0]
	s_lshl_b32 s4, s14, 2
	v_pk_add_f32 v[132:133], v[132:133], 1.0 op_sel_hi:[1,0]
	v_pk_add_f32 v[128:129], v[128:129], 1.0 op_sel_hi:[1,0]
	v_rcp_f32_e32 v132, v132
	v_rcp_f32_e32 v133, v133
	v_rcp_f32_e32 v134, v128
	v_rcp_f32_e32 v135, v129
	v_exp_f32_e32 v156, v156
	v_exp_f32_e32 v157, v157
	s_or_b32 s4, s4, s18
	s_mov_b32 s18, 0x4b000000
	v_mov_b64_e32 v[128:129], s[18:19]
	v_pk_fma_f32 v[134:135], v[134:135], s[62:63], v[128:129] op_sel_hi:[1,0,0]
	v_pk_fma_f32 v[132:133], v[132:133], s[62:63], v[128:129] op_sel_hi:[1,0,0]
	v_pk_add_f32 v[156:157], v[156:157], 1.0 op_sel_hi:[1,0]
	v_max_f32_e32 v132, 0x4b000001, v132
	v_max_f32_e32 v133, 0x4b000001, v133
	v_max_f32_e32 v134, 0x4b000001, v134
	v_max_f32_e32 v135, 0x4b000001, v135
	v_rcp_f32_e32 v156, v156
	v_rcp_f32_e32 v157, v157
	v_perm_b32 v132, v133, v132, s46
	v_perm_b32 v133, v135, v134, s46
	v_pk_mul_f32 v[134:135], v[122:123], s[60:61] op_sel_hi:[1,0]
	v_pk_fma_f32 v[156:157], v[156:157], s[62:63], v[128:129] op_sel_hi:[1,0,0]
	v_exp_f32_e32 v134, v134
	v_exp_f32_e32 v135, v135
	v_perm_b32 v132, v133, v132, s47
	v_max_f32_e32 v133, 0x4b000001, v156
	v_max_f32_e32 v151, 0x4b000001, v157
	v_pk_mul_f32 v[156:157], v[116:117], s[60:61] op_sel_hi:[1,0]
	v_pk_add_f32 v[134:135], v[134:135], 1.0 op_sel_hi:[1,0]
	v_exp_f32_e32 v156, v156
	v_exp_f32_e32 v157, v157
	v_rcp_f32_e32 v134, v134
	v_rcp_f32_e32 v135, v135
	v_perm_b32 v133, v151, v133, s46
	v_pk_add_f32 v[156:157], v[156:157], 1.0 op_sel_hi:[1,0]
	v_pk_mul_f32 v[158:159], v[112:113], s[60:61] op_sel_hi:[1,0]
	v_pk_fma_f32 v[134:135], v[134:135], s[62:63], v[128:129] op_sel_hi:[1,0,0]
	v_rcp_f32_e32 v156, v156
	v_rcp_f32_e32 v157, v157
	v_max_f32_e32 v134, 0x4b000001, v134
	v_max_f32_e32 v135, 0x4b000001, v135
	v_perm_b32 v134, v135, v134, s46
	v_perm_b32 v133, v134, v133, s47
	v_pk_mul_f32 v[134:135], v[118:119], s[60:61] op_sel_hi:[1,0]
	v_pk_fma_f32 v[156:157], v[156:157], s[62:63], v[128:129] op_sel_hi:[1,0,0]
	v_exp_f32_e32 v134, v134
	v_exp_f32_e32 v135, v135
	v_max_f32_e32 v151, 0x4b000001, v156
	v_max_f32_e32 v153, 0x4b000001, v157
	v_pk_mul_f32 v[156:157], v[114:115], s[60:61] op_sel_hi:[1,0]
	v_exp_f32_e32 v158, v158
	v_exp_f32_e32 v159, v159
	v_exp_f32_e32 v156, v156
	v_exp_f32_e32 v157, v157
	v_pk_add_f32 v[134:135], v[134:135], 1.0 op_sel_hi:[1,0]
	v_pk_add_f32 v[158:159], v[158:159], 1.0 op_sel_hi:[1,0]
	v_rcp_f32_e32 v134, v134
	v_rcp_f32_e32 v135, v135
	v_pk_add_f32 v[156:157], v[156:157], 1.0 op_sel_hi:[1,0]
	v_rcp_f32_e32 v158, v158
	v_rcp_f32_e32 v159, v159
	v_rcp_f32_e32 v156, v156
	v_rcp_f32_e32 v157, v157
	v_pk_fma_f32 v[134:135], v[134:135], s[62:63], v[128:129] op_sel_hi:[1,0,0]
	s_ashr_i32 s5, s4, 31
	v_max_f32_e32 v134, 0x4b000001, v134
	v_max_f32_e32 v135, 0x4b000001, v135
	v_perm_b32 v151, v153, v151, s46
	v_perm_b32 v134, v135, v134, s46
	v_pk_fma_f32 v[156:157], v[156:157], s[62:63], v[128:129] op_sel_hi:[1,0,0]
	v_pk_fma_f32 v[158:159], v[158:159], s[62:63], v[128:129] op_sel_hi:[1,0,0]
	s_lshl_b64 s[4:5], s[4:5], 16
	v_perm_b32 v134, v134, v151, s47
	v_max_f32_e32 v135, 0x4b000001, v158
	v_max_f32_e32 v151, 0x4b000001, v159
	v_max_f32_e32 v153, 0x4b000001, v156
	v_max_f32_e32 v155, 0x4b000001, v157
	s_add_u32 s4, s72, s4
	v_perm_b32 v135, v151, v135, s46
	v_perm_b32 v151, v155, v153, s46
	s_addc_u32 s5, s73, s5
	v_lshl_add_u32 v144, v185, 4, s90
	v_perm_b32 v135, v151, v135, s47
	global_store_dwordx4 v144, v[132:135], s[4:5] nt
	v_pk_mul_f32 v[156:157], v[104:105], s[60:61] op_sel_hi:[1,0]
	v_pk_mul_f32 v[158:159], v[96:97], s[60:61] op_sel_hi:[1,0]
	v_pk_mul_f32 v[132:133], v[110:111], s[60:61] op_sel_hi:[1,0]
	v_pk_mul_f32 v[134:135], v[108:109], s[60:61] op_sel_hi:[1,0]
	v_exp_f32_e32 v132, v132
	v_exp_f32_e32 v134, v134
	v_exp_f32_e32 v135, v135
	v_exp_f32_e32 v133, v133
	v_exp_f32_e32 v156, v156
	v_exp_f32_e32 v157, v157
	v_pk_add_f32 v[134:135], v[134:135], 1.0 op_sel_hi:[1,0]
	v_pk_add_f32 v[132:133], v[132:133], 1.0 op_sel_hi:[1,0]
	v_rcp_f32_e32 v134, v134
	v_rcp_f32_e32 v135, v135
	v_rcp_f32_e32 v132, v132
	v_rcp_f32_e32 v133, v133
	v_pk_add_f32 v[156:157], v[156:157], 1.0 op_sel_hi:[1,0]
	v_pk_fma_f32 v[134:135], v[134:135], s[62:63], v[128:129] op_sel_hi:[1,0,0]
	v_rcp_f32_e32 v156, v156
	v_pk_fma_f32 v[132:133], v[132:133], s[62:63], v[128:129] op_sel_hi:[1,0,0]
	v_max_f32_e32 v134, 0x4b000001, v134
	v_max_f32_e32 v135, 0x4b000001, v135
	v_max_f32_e32 v132, 0x4b000001, v132
	v_max_f32_e32 v133, 0x4b000001, v133
	v_perm_b32 v134, v135, v134, s46
	v_perm_b32 v132, v133, v132, s46
	v_rcp_f32_e32 v157, v157
	v_perm_b32 v132, v132, v134, s47
	v_pk_mul_f32 v[134:135], v[106:107], s[60:61] op_sel_hi:[1,0]
	v_exp_f32_e32 v158, v158
	v_exp_f32_e32 v134, v134
	v_exp_f32_e32 v135, v135
	v_pk_fma_f32 v[156:157], v[156:157], s[62:63], v[128:129] op_sel_hi:[1,0,0]
	v_exp_f32_e32 v159, v159
	v_max_f32_e32 v133, 0x4b000001, v156
	v_max_f32_e32 v151, 0x4b000001, v157
	v_pk_mul_f32 v[156:157], v[100:101], s[60:61] op_sel_hi:[1,0]
	v_pk_add_f32 v[134:135], v[134:135], 1.0 op_sel_hi:[1,0]
	v_exp_f32_e32 v156, v156
	v_exp_f32_e32 v157, v157
	v_rcp_f32_e32 v134, v134
	v_rcp_f32_e32 v135, v135
	v_perm_b32 v133, v151, v133, s46
	v_pk_add_f32 v[156:157], v[156:157], 1.0 op_sel_hi:[1,0]
	v_pk_add_f32 v[158:159], v[158:159], 1.0 op_sel_hi:[1,0]
	v_pk_fma_f32 v[134:135], v[134:135], s[62:63], v[128:129] op_sel_hi:[1,0,0]
	v_rcp_f32_e32 v156, v156
	v_rcp_f32_e32 v157, v157
	v_max_f32_e32 v134, 0x4b000001, v134
	v_max_f32_e32 v135, 0x4b000001, v135
	v_perm_b32 v134, v135, v134, s46
	v_perm_b32 v133, v134, v133, s47
	v_pk_mul_f32 v[134:135], v[102:103], s[60:61] op_sel_hi:[1,0]
	v_pk_fma_f32 v[156:157], v[156:157], s[62:63], v[128:129] op_sel_hi:[1,0,0]
	v_exp_f32_e32 v134, v134
	v_exp_f32_e32 v135, v135
	v_max_f32_e32 v151, 0x4b000001, v156
	v_max_f32_e32 v153, 0x4b000001, v157
	v_pk_mul_f32 v[156:157], v[98:99], s[60:61] op_sel_hi:[1,0]
	v_pk_add_f32 v[134:135], v[134:135], 1.0 op_sel_hi:[1,0]
	v_exp_f32_e32 v156, v156
	v_exp_f32_e32 v157, v157
	v_rcp_f32_e32 v134, v134
	v_rcp_f32_e32 v135, v135
	v_rcp_f32_e32 v158, v158
	v_pk_add_f32 v[156:157], v[156:157], 1.0 op_sel_hi:[1,0]
	v_rcp_f32_e32 v159, v159
	v_rcp_f32_e32 v156, v156
	v_rcp_f32_e32 v157, v157
	v_pk_fma_f32 v[134:135], v[134:135], s[62:63], v[128:129] op_sel_hi:[1,0,0]
	v_perm_b32 v151, v153, v151, s46
	v_max_f32_e32 v134, 0x4b000001, v134
	v_max_f32_e32 v135, 0x4b000001, v135
	v_perm_b32 v134, v135, v134, s46
	v_pk_fma_f32 v[156:157], v[156:157], s[62:63], v[128:129] op_sel_hi:[1,0,0]
	v_pk_fma_f32 v[158:159], v[158:159], s[62:63], v[128:129] op_sel_hi:[1,0,0]
	v_perm_b32 v134, v134, v151, s47
	v_max_f32_e32 v135, 0x4b000001, v158
	v_max_f32_e32 v151, 0x4b000001, v159
	v_max_f32_e32 v153, 0x4b000001, v156
	v_max_f32_e32 v155, 0x4b000001, v157
	v_perm_b32 v135, v151, v135, s46
	v_perm_b32 v151, v155, v153, s46
	v_perm_b32 v135, v151, v135, s47
	global_store_dwordx4 v144, v[132:135], s[4:5] offset:1024 nt
	v_pk_mul_f32 v[156:157], v[88:89], s[60:61] op_sel_hi:[1,0]
	v_pk_mul_f32 v[158:159], v[80:81], s[60:61] op_sel_hi:[1,0]
	v_pk_mul_f32 v[132:133], v[94:95], s[60:61] op_sel_hi:[1,0]
	v_pk_mul_f32 v[134:135], v[92:93], s[60:61] op_sel_hi:[1,0]
	v_exp_f32_e32 v132, v132
	v_exp_f32_e32 v134, v134
	v_exp_f32_e32 v135, v135
	v_exp_f32_e32 v133, v133
	v_exp_f32_e32 v156, v156
	v_exp_f32_e32 v157, v157
	v_pk_add_f32 v[134:135], v[134:135], 1.0 op_sel_hi:[1,0]
	v_pk_add_f32 v[132:133], v[132:133], 1.0 op_sel_hi:[1,0]
	v_rcp_f32_e32 v134, v134
	v_rcp_f32_e32 v135, v135
	v_rcp_f32_e32 v132, v132
	v_rcp_f32_e32 v133, v133
	v_pk_add_f32 v[156:157], v[156:157], 1.0 op_sel_hi:[1,0]
	v_pk_fma_f32 v[134:135], v[134:135], s[62:63], v[128:129] op_sel_hi:[1,0,0]
	v_rcp_f32_e32 v156, v156
	v_pk_fma_f32 v[132:133], v[132:133], s[62:63], v[128:129] op_sel_hi:[1,0,0]
	v_max_f32_e32 v134, 0x4b000001, v134
	v_max_f32_e32 v135, 0x4b000001, v135
	v_max_f32_e32 v132, 0x4b000001, v132
	v_max_f32_e32 v133, 0x4b000001, v133
	v_perm_b32 v134, v135, v134, s46
	v_perm_b32 v132, v133, v132, s46
	v_rcp_f32_e32 v157, v157
	v_perm_b32 v132, v132, v134, s47
	v_pk_mul_f32 v[134:135], v[90:91], s[60:61] op_sel_hi:[1,0]
	v_exp_f32_e32 v158, v158
	v_exp_f32_e32 v134, v134
	v_exp_f32_e32 v135, v135
	v_pk_fma_f32 v[156:157], v[156:157], s[62:63], v[128:129] op_sel_hi:[1,0,0]
	v_exp_f32_e32 v159, v159
	v_max_f32_e32 v133, 0x4b000001, v156
	v_max_f32_e32 v151, 0x4b000001, v157
	v_pk_mul_f32 v[156:157], v[84:85], s[60:61] op_sel_hi:[1,0]
	v_pk_add_f32 v[134:135], v[134:135], 1.0 op_sel_hi:[1,0]
	v_exp_f32_e32 v156, v156
	v_exp_f32_e32 v157, v157
	v_rcp_f32_e32 v134, v134
	v_rcp_f32_e32 v135, v135
	v_perm_b32 v133, v151, v133, s46
	v_pk_add_f32 v[156:157], v[156:157], 1.0 op_sel_hi:[1,0]
	v_pk_add_f32 v[158:159], v[158:159], 1.0 op_sel_hi:[1,0]
	v_pk_fma_f32 v[134:135], v[134:135], s[62:63], v[128:129] op_sel_hi:[1,0,0]
	v_rcp_f32_e32 v156, v156
	v_rcp_f32_e32 v157, v157
	v_max_f32_e32 v134, 0x4b000001, v134
	v_max_f32_e32 v135, 0x4b000001, v135
	v_perm_b32 v134, v135, v134, s46
	v_perm_b32 v133, v134, v133, s47
	v_pk_mul_f32 v[134:135], v[86:87], s[60:61] op_sel_hi:[1,0]
	v_pk_fma_f32 v[156:157], v[156:157], s[62:63], v[128:129] op_sel_hi:[1,0,0]
	v_exp_f32_e32 v134, v134
	v_exp_f32_e32 v135, v135
	v_max_f32_e32 v151, 0x4b000001, v156
	v_max_f32_e32 v153, 0x4b000001, v157
	v_pk_mul_f32 v[156:157], v[82:83], s[60:61] op_sel_hi:[1,0]
	v_pk_add_f32 v[134:135], v[134:135], 1.0 op_sel_hi:[1,0]
	v_exp_f32_e32 v156, v156
	v_exp_f32_e32 v157, v157
	v_rcp_f32_e32 v134, v134
	v_rcp_f32_e32 v135, v135
	v_rcp_f32_e32 v158, v158
	v_pk_add_f32 v[156:157], v[156:157], 1.0 op_sel_hi:[1,0]
	v_rcp_f32_e32 v159, v159
	v_rcp_f32_e32 v156, v156
	v_rcp_f32_e32 v157, v157
	v_pk_fma_f32 v[134:135], v[134:135], s[62:63], v[128:129] op_sel_hi:[1,0,0]
	v_perm_b32 v151, v153, v151, s46
	v_max_f32_e32 v134, 0x4b000001, v134
	v_max_f32_e32 v135, 0x4b000001, v135
	v_perm_b32 v134, v135, v134, s46
	v_pk_fma_f32 v[156:157], v[156:157], s[62:63], v[128:129] op_sel_hi:[1,0,0]
	v_pk_fma_f32 v[158:159], v[158:159], s[62:63], v[128:129] op_sel_hi:[1,0,0]
	v_perm_b32 v134, v134, v151, s47
	v_max_f32_e32 v135, 0x4b000001, v158
	v_max_f32_e32 v151, 0x4b000001, v159
	v_max_f32_e32 v153, 0x4b000001, v156
	v_max_f32_e32 v155, 0x4b000001, v157
	v_perm_b32 v135, v151, v135, s46
	v_perm_b32 v151, v155, v153, s46
	v_perm_b32 v135, v151, v135, s47
	global_store_dwordx4 v144, v[132:135], s[4:5] offset:2048 nt
	v_pk_mul_f32 v[156:157], v[72:73], s[60:61] op_sel_hi:[1,0]
	v_pk_mul_f32 v[158:159], v[64:65], s[60:61] op_sel_hi:[1,0]
	v_pk_mul_f32 v[132:133], v[78:79], s[60:61] op_sel_hi:[1,0]
	v_pk_mul_f32 v[134:135], v[76:77], s[60:61] op_sel_hi:[1,0]
	v_exp_f32_e32 v132, v132
	v_exp_f32_e32 v134, v134
	v_exp_f32_e32 v135, v135
	v_exp_f32_e32 v133, v133
	v_exp_f32_e32 v156, v156
	v_exp_f32_e32 v157, v157
	v_pk_add_f32 v[134:135], v[134:135], 1.0 op_sel_hi:[1,0]
	v_pk_add_f32 v[132:133], v[132:133], 1.0 op_sel_hi:[1,0]
	v_rcp_f32_e32 v134, v134
	v_rcp_f32_e32 v135, v135
	v_rcp_f32_e32 v132, v132
	v_rcp_f32_e32 v133, v133
	v_pk_add_f32 v[156:157], v[156:157], 1.0 op_sel_hi:[1,0]
	v_pk_fma_f32 v[134:135], v[134:135], s[62:63], v[128:129] op_sel_hi:[1,0,0]
	v_rcp_f32_e32 v156, v156
	v_pk_fma_f32 v[132:133], v[132:133], s[62:63], v[128:129] op_sel_hi:[1,0,0]
	v_max_f32_e32 v134, 0x4b000001, v134
	v_max_f32_e32 v135, 0x4b000001, v135
	v_max_f32_e32 v132, 0x4b000001, v132
	v_max_f32_e32 v133, 0x4b000001, v133
	v_perm_b32 v134, v135, v134, s46
	v_perm_b32 v132, v133, v132, s46
	v_rcp_f32_e32 v157, v157
	v_perm_b32 v132, v132, v134, s47
	v_pk_mul_f32 v[134:135], v[74:75], s[60:61] op_sel_hi:[1,0]
	v_exp_f32_e32 v158, v158
	v_exp_f32_e32 v134, v134
	v_exp_f32_e32 v135, v135
	v_pk_fma_f32 v[156:157], v[156:157], s[62:63], v[128:129] op_sel_hi:[1,0,0]
	v_exp_f32_e32 v159, v159
	v_max_f32_e32 v133, 0x4b000001, v156
	v_max_f32_e32 v151, 0x4b000001, v157
	v_pk_mul_f32 v[156:157], v[68:69], s[60:61] op_sel_hi:[1,0]
	v_pk_add_f32 v[134:135], v[134:135], 1.0 op_sel_hi:[1,0]
	v_exp_f32_e32 v156, v156
	v_exp_f32_e32 v157, v157
	v_rcp_f32_e32 v134, v134
	v_rcp_f32_e32 v135, v135
	v_perm_b32 v133, v151, v133, s46
	v_pk_add_f32 v[156:157], v[156:157], 1.0 op_sel_hi:[1,0]
	v_pk_add_f32 v[158:159], v[158:159], 1.0 op_sel_hi:[1,0]
	v_pk_fma_f32 v[134:135], v[134:135], s[62:63], v[128:129] op_sel_hi:[1,0,0]
	v_rcp_f32_e32 v156, v156
	v_rcp_f32_e32 v157, v157
	v_max_f32_e32 v134, 0x4b000001, v134
	v_max_f32_e32 v135, 0x4b000001, v135
	v_perm_b32 v134, v135, v134, s46
	v_perm_b32 v133, v134, v133, s47
	v_pk_mul_f32 v[134:135], v[70:71], s[60:61] op_sel_hi:[1,0]
	v_pk_fma_f32 v[156:157], v[156:157], s[62:63], v[128:129] op_sel_hi:[1,0,0]
	v_exp_f32_e32 v134, v134
	v_exp_f32_e32 v135, v135
	v_max_f32_e32 v151, 0x4b000001, v156
	v_max_f32_e32 v153, 0x4b000001, v157
	v_pk_mul_f32 v[156:157], v[66:67], s[60:61] op_sel_hi:[1,0]
	v_pk_add_f32 v[134:135], v[134:135], 1.0 op_sel_hi:[1,0]
	v_exp_f32_e32 v156, v156
	v_exp_f32_e32 v157, v157
	v_rcp_f32_e32 v134, v134
	v_rcp_f32_e32 v135, v135
	v_rcp_f32_e32 v158, v158
	v_pk_add_f32 v[156:157], v[156:157], 1.0 op_sel_hi:[1,0]
	v_rcp_f32_e32 v159, v159
	v_rcp_f32_e32 v156, v156
	v_rcp_f32_e32 v157, v157
	v_pk_fma_f32 v[134:135], v[134:135], s[62:63], v[128:129] op_sel_hi:[1,0,0]
	v_perm_b32 v151, v153, v151, s46
	v_max_f32_e32 v134, 0x4b000001, v134
	v_max_f32_e32 v135, 0x4b000001, v135
	v_perm_b32 v134, v135, v134, s46
	v_pk_fma_f32 v[156:157], v[156:157], s[62:63], v[128:129] op_sel_hi:[1,0,0]
	v_pk_fma_f32 v[158:159], v[158:159], s[62:63], v[128:129] op_sel_hi:[1,0,0]
	v_perm_b32 v134, v134, v151, s47
	v_max_f32_e32 v135, 0x4b000001, v158
	v_max_f32_e32 v151, 0x4b000001, v159
	v_max_f32_e32 v153, 0x4b000001, v156
	v_max_f32_e32 v155, 0x4b000001, v157
	v_perm_b32 v135, v151, v135, s46
	v_perm_b32 v151, v155, v153, s46
	v_perm_b32 v135, v151, v135, s47
	global_store_dwordx4 v144, v[132:135], s[4:5] offset:3072 nt
	v_pk_mul_f32 v[156:157], v[56:57], s[60:61] op_sel_hi:[1,0]
	v_lshl_add_u64 v[130:131], s[4:5], 0, v[144:145]
	v_pk_mul_f32 v[132:133], v[62:63], s[60:61] op_sel_hi:[1,0]
	v_pk_mul_f32 v[134:135], v[60:61], s[60:61] op_sel_hi:[1,0]
	v_exp_f32_e32 v132, v132
	v_exp_f32_e32 v134, v134
	v_exp_f32_e32 v135, v135
	v_exp_f32_e32 v133, v133
	v_exp_f32_e32 v156, v156
	v_exp_f32_e32 v157, v157
	v_pk_add_f32 v[134:135], v[134:135], 1.0 op_sel_hi:[1,0]
	v_pk_add_f32 v[132:133], v[132:133], 1.0 op_sel_hi:[1,0]
	v_rcp_f32_e32 v134, v134
	v_rcp_f32_e32 v135, v135
	v_rcp_f32_e32 v132, v132
	v_rcp_f32_e32 v133, v133
	v_pk_add_f32 v[156:157], v[156:157], 1.0 op_sel_hi:[1,0]
	v_pk_fma_f32 v[134:135], v[134:135], s[62:63], v[128:129] op_sel_hi:[1,0,0]
	v_rcp_f32_e32 v156, v156
	v_pk_fma_f32 v[132:133], v[132:133], s[62:63], v[128:129] op_sel_hi:[1,0,0]
	v_max_f32_e32 v134, 0x4b000001, v134
	v_max_f32_e32 v135, 0x4b000001, v135
	v_max_f32_e32 v132, 0x4b000001, v132
	v_max_f32_e32 v133, 0x4b000001, v133
	v_perm_b32 v134, v135, v134, s46
	v_perm_b32 v132, v133, v132, s46
	v_rcp_f32_e32 v157, v157
	v_perm_b32 v132, v132, v134, s47
	v_pk_mul_f32 v[134:135], v[58:59], s[60:61] op_sel_hi:[1,0]
	v_pk_mul_f32 v[158:159], v[48:49], s[60:61] op_sel_hi:[1,0]
	v_exp_f32_e32 v134, v134
	v_exp_f32_e32 v135, v135
	v_pk_fma_f32 v[156:157], v[156:157], s[62:63], v[128:129] op_sel_hi:[1,0,0]
	v_exp_f32_e32 v158, v158
	v_max_f32_e32 v133, 0x4b000001, v156
	v_max_f32_e32 v144, 0x4b000001, v157
	v_pk_mul_f32 v[156:157], v[52:53], s[60:61] op_sel_hi:[1,0]
	v_pk_add_f32 v[134:135], v[134:135], 1.0 op_sel_hi:[1,0]
	v_exp_f32_e32 v156, v156
	v_exp_f32_e32 v157, v157
	v_rcp_f32_e32 v134, v134
	v_rcp_f32_e32 v135, v135
	v_perm_b32 v133, v144, v133, s46
	v_pk_add_f32 v[156:157], v[156:157], 1.0 op_sel_hi:[1,0]
	v_exp_f32_e32 v159, v159
	v_pk_fma_f32 v[134:135], v[134:135], s[62:63], v[128:129] op_sel_hi:[1,0,0]
	v_rcp_f32_e32 v156, v156
	v_rcp_f32_e32 v157, v157
	v_max_f32_e32 v134, 0x4b000001, v134
	v_max_f32_e32 v135, 0x4b000001, v135
	v_perm_b32 v134, v135, v134, s46
	v_perm_b32 v133, v134, v133, s47
	v_pk_mul_f32 v[134:135], v[54:55], s[60:61] op_sel_hi:[1,0]
	v_pk_fma_f32 v[156:157], v[156:157], s[62:63], v[128:129] op_sel_hi:[1,0,0]
	v_exp_f32_e32 v134, v134
	v_exp_f32_e32 v135, v135
	v_max_f32_e32 v144, 0x4b000001, v156
	v_max_f32_e32 v151, 0x4b000001, v157
	v_pk_mul_f32 v[156:157], v[50:51], s[60:61] op_sel_hi:[1,0]
	v_pk_add_f32 v[134:135], v[134:135], 1.0 op_sel_hi:[1,0]
	v_exp_f32_e32 v156, v156
	v_exp_f32_e32 v157, v157
	v_rcp_f32_e32 v134, v134
	v_rcp_f32_e32 v135, v135
	v_pk_add_f32 v[158:159], v[158:159], 1.0 op_sel_hi:[1,0]
	v_pk_add_f32 v[156:157], v[156:157], 1.0 op_sel_hi:[1,0]
	v_rcp_f32_e32 v158, v158
	v_rcp_f32_e32 v159, v159
	v_rcp_f32_e32 v156, v156
	v_rcp_f32_e32 v157, v157
	v_pk_fma_f32 v[134:135], v[134:135], s[62:63], v[128:129] op_sel_hi:[1,0,0]
	v_perm_b32 v144, v151, v144, s46
	v_max_f32_e32 v134, 0x4b000001, v134
	v_max_f32_e32 v135, 0x4b000001, v135
	v_perm_b32 v134, v135, v134, s46
	v_pk_fma_f32 v[156:157], v[156:157], s[62:63], v[128:129] op_sel_hi:[1,0,0]
	v_pk_fma_f32 v[158:159], v[158:159], s[62:63], v[128:129] op_sel_hi:[1,0,0]
	v_perm_b32 v134, v134, v144, s47
	v_max_f32_e32 v135, 0x4b000001, v158
	v_max_f32_e32 v144, 0x4b000001, v159
	v_max_f32_e32 v151, 0x4b000001, v156
	v_max_f32_e32 v153, 0x4b000001, v157
	s_movk_i32 s4, 0x1000
	v_perm_b32 v135, v144, v135, s46
	v_perm_b32 v144, v153, v151, s46
	v_add_co_u32_e32 v130, vcc, s4, v130
	v_perm_b32 v135, v144, v135, s47
	s_nop 0
	v_addc_co_u32_e32 v131, vcc, 0, v131, vcc
	global_store_dwordx4 v[130:131], v[132:135], off nt
	v_pk_mul_f32 v[156:157], v[40:41], s[60:61] op_sel_hi:[1,0]
	v_pk_mul_f32 v[158:159], v[32:33], s[60:61] op_sel_hi:[1,0]
	v_pk_mul_f32 v[132:133], v[46:47], s[60:61] op_sel_hi:[1,0]
	v_pk_mul_f32 v[134:135], v[44:45], s[60:61] op_sel_hi:[1,0]
	v_exp_f32_e32 v132, v132
	v_exp_f32_e32 v134, v134
	v_exp_f32_e32 v135, v135
	v_exp_f32_e32 v133, v133
	v_exp_f32_e32 v156, v156
	v_exp_f32_e32 v157, v157
	v_pk_add_f32 v[134:135], v[134:135], 1.0 op_sel_hi:[1,0]
	v_pk_add_f32 v[132:133], v[132:133], 1.0 op_sel_hi:[1,0]
	v_rcp_f32_e32 v134, v134
	v_rcp_f32_e32 v135, v135
	v_rcp_f32_e32 v132, v132
	v_rcp_f32_e32 v133, v133
	v_pk_add_f32 v[156:157], v[156:157], 1.0 op_sel_hi:[1,0]
	v_pk_fma_f32 v[134:135], v[134:135], s[62:63], v[128:129] op_sel_hi:[1,0,0]
	v_rcp_f32_e32 v156, v156
	v_pk_fma_f32 v[132:133], v[132:133], s[62:63], v[128:129] op_sel_hi:[1,0,0]
	v_max_f32_e32 v134, 0x4b000001, v134
	v_max_f32_e32 v135, 0x4b000001, v135
	v_max_f32_e32 v132, 0x4b000001, v132
	v_max_f32_e32 v133, 0x4b000001, v133
	v_perm_b32 v134, v135, v134, s46
	v_perm_b32 v132, v133, v132, s46
	v_rcp_f32_e32 v157, v157
	v_perm_b32 v132, v132, v134, s47
	v_pk_mul_f32 v[134:135], v[42:43], s[60:61] op_sel_hi:[1,0]
	v_exp_f32_e32 v158, v158
	v_exp_f32_e32 v134, v134
	v_exp_f32_e32 v135, v135
	v_pk_fma_f32 v[156:157], v[156:157], s[62:63], v[128:129] op_sel_hi:[1,0,0]
	v_exp_f32_e32 v159, v159
	v_max_f32_e32 v133, 0x4b000001, v156
	v_max_f32_e32 v144, 0x4b000001, v157
	v_pk_mul_f32 v[156:157], v[36:37], s[60:61] op_sel_hi:[1,0]
	v_pk_add_f32 v[134:135], v[134:135], 1.0 op_sel_hi:[1,0]
	v_exp_f32_e32 v156, v156
	v_exp_f32_e32 v157, v157
	v_rcp_f32_e32 v134, v134
	v_rcp_f32_e32 v135, v135
	v_perm_b32 v133, v144, v133, s46
	v_pk_add_f32 v[156:157], v[156:157], 1.0 op_sel_hi:[1,0]
	v_pk_add_f32 v[158:159], v[158:159], 1.0 op_sel_hi:[1,0]
	v_pk_fma_f32 v[134:135], v[134:135], s[62:63], v[128:129] op_sel_hi:[1,0,0]
	v_rcp_f32_e32 v156, v156
	v_rcp_f32_e32 v157, v157
	v_max_f32_e32 v134, 0x4b000001, v134
	v_max_f32_e32 v135, 0x4b000001, v135
	v_perm_b32 v134, v135, v134, s46
	v_perm_b32 v133, v134, v133, s47
	v_pk_mul_f32 v[134:135], v[38:39], s[60:61] op_sel_hi:[1,0]
	v_pk_fma_f32 v[156:157], v[156:157], s[62:63], v[128:129] op_sel_hi:[1,0,0]
	v_exp_f32_e32 v134, v134
	v_exp_f32_e32 v135, v135
	v_max_f32_e32 v144, 0x4b000001, v156
	v_max_f32_e32 v151, 0x4b000001, v157
	v_pk_mul_f32 v[156:157], v[34:35], s[60:61] op_sel_hi:[1,0]
	v_pk_add_f32 v[134:135], v[134:135], 1.0 op_sel_hi:[1,0]
	v_exp_f32_e32 v156, v156
	v_exp_f32_e32 v157, v157
	v_rcp_f32_e32 v134, v134
	v_rcp_f32_e32 v135, v135
	v_rcp_f32_e32 v158, v158
	v_pk_add_f32 v[156:157], v[156:157], 1.0 op_sel_hi:[1,0]
	v_rcp_f32_e32 v159, v159
	v_rcp_f32_e32 v156, v156
	v_rcp_f32_e32 v157, v157
	v_pk_fma_f32 v[134:135], v[134:135], s[62:63], v[128:129] op_sel_hi:[1,0,0]
	v_perm_b32 v144, v151, v144, s46
	v_max_f32_e32 v134, 0x4b000001, v134
	v_max_f32_e32 v135, 0x4b000001, v135
	v_perm_b32 v134, v135, v134, s46
	v_pk_fma_f32 v[156:157], v[156:157], s[62:63], v[128:129] op_sel_hi:[1,0,0]
	v_pk_fma_f32 v[158:159], v[158:159], s[62:63], v[128:129] op_sel_hi:[1,0,0]
	v_perm_b32 v134, v134, v144, s47
	v_max_f32_e32 v135, 0x4b000001, v158
	v_max_f32_e32 v144, 0x4b000001, v159
	v_max_f32_e32 v151, 0x4b000001, v156
	v_max_f32_e32 v153, 0x4b000001, v157
	v_perm_b32 v135, v144, v135, s46
	v_perm_b32 v144, v153, v151, s46
	v_perm_b32 v135, v144, v135, s47
	global_store_dwordx4 v[130:131], v[132:135], off offset:1024 nt
	v_pk_mul_f32 v[156:157], v[24:25], s[60:61] op_sel_hi:[1,0]
	v_pk_mul_f32 v[158:159], v[16:17], s[60:61] op_sel_hi:[1,0]
	v_pk_mul_f32 v[132:133], v[30:31], s[60:61] op_sel_hi:[1,0]
	v_pk_mul_f32 v[134:135], v[28:29], s[60:61] op_sel_hi:[1,0]
	v_exp_f32_e32 v132, v132
	v_exp_f32_e32 v134, v134
	v_exp_f32_e32 v135, v135
	v_exp_f32_e32 v133, v133
	v_exp_f32_e32 v156, v156
	v_exp_f32_e32 v157, v157
	v_pk_add_f32 v[134:135], v[134:135], 1.0 op_sel_hi:[1,0]
	v_pk_add_f32 v[132:133], v[132:133], 1.0 op_sel_hi:[1,0]
	v_rcp_f32_e32 v134, v134
	v_rcp_f32_e32 v135, v135
	v_rcp_f32_e32 v132, v132
	v_rcp_f32_e32 v133, v133
	v_pk_add_f32 v[156:157], v[156:157], 1.0 op_sel_hi:[1,0]
	v_pk_fma_f32 v[134:135], v[134:135], s[62:63], v[128:129] op_sel_hi:[1,0,0]
	v_rcp_f32_e32 v156, v156
	v_pk_fma_f32 v[132:133], v[132:133], s[62:63], v[128:129] op_sel_hi:[1,0,0]
	v_max_f32_e32 v134, 0x4b000001, v134
	v_max_f32_e32 v135, 0x4b000001, v135
	v_max_f32_e32 v132, 0x4b000001, v132
	v_max_f32_e32 v133, 0x4b000001, v133
	v_perm_b32 v134, v135, v134, s46
	v_perm_b32 v132, v133, v132, s46
	v_rcp_f32_e32 v157, v157
	v_perm_b32 v132, v132, v134, s47
	v_pk_mul_f32 v[134:135], v[26:27], s[60:61] op_sel_hi:[1,0]
	v_exp_f32_e32 v158, v158
	v_exp_f32_e32 v134, v134
	v_exp_f32_e32 v135, v135
	v_pk_fma_f32 v[156:157], v[156:157], s[62:63], v[128:129] op_sel_hi:[1,0,0]
	v_exp_f32_e32 v159, v159
	v_max_f32_e32 v133, 0x4b000001, v156
	v_max_f32_e32 v144, 0x4b000001, v157
	v_pk_mul_f32 v[156:157], v[20:21], s[60:61] op_sel_hi:[1,0]
	v_pk_add_f32 v[134:135], v[134:135], 1.0 op_sel_hi:[1,0]
	v_exp_f32_e32 v156, v156
	v_exp_f32_e32 v157, v157
	v_rcp_f32_e32 v134, v134
	v_rcp_f32_e32 v135, v135
	v_perm_b32 v133, v144, v133, s46
	v_pk_add_f32 v[156:157], v[156:157], 1.0 op_sel_hi:[1,0]
	v_pk_add_f32 v[158:159], v[158:159], 1.0 op_sel_hi:[1,0]
	v_pk_fma_f32 v[134:135], v[134:135], s[62:63], v[128:129] op_sel_hi:[1,0,0]
	v_rcp_f32_e32 v156, v156
	v_rcp_f32_e32 v157, v157
	v_max_f32_e32 v134, 0x4b000001, v134
	v_max_f32_e32 v135, 0x4b000001, v135
	v_perm_b32 v134, v135, v134, s46
	v_perm_b32 v133, v134, v133, s47
	v_pk_mul_f32 v[134:135], v[22:23], s[60:61] op_sel_hi:[1,0]
	v_pk_fma_f32 v[156:157], v[156:157], s[62:63], v[128:129] op_sel_hi:[1,0,0]
	v_exp_f32_e32 v134, v134
	v_exp_f32_e32 v135, v135
	v_max_f32_e32 v144, 0x4b000001, v156
	v_max_f32_e32 v151, 0x4b000001, v157
	v_pk_mul_f32 v[156:157], v[18:19], s[60:61] op_sel_hi:[1,0]
	v_pk_add_f32 v[134:135], v[134:135], 1.0 op_sel_hi:[1,0]
	v_exp_f32_e32 v156, v156
	v_exp_f32_e32 v157, v157
	v_rcp_f32_e32 v134, v134
	v_rcp_f32_e32 v135, v135
	v_rcp_f32_e32 v158, v158
	v_pk_add_f32 v[156:157], v[156:157], 1.0 op_sel_hi:[1,0]
	v_rcp_f32_e32 v159, v159
	v_rcp_f32_e32 v156, v156
	v_rcp_f32_e32 v157, v157
	v_pk_fma_f32 v[134:135], v[134:135], s[62:63], v[128:129] op_sel_hi:[1,0,0]
	v_perm_b32 v144, v151, v144, s46
	v_max_f32_e32 v134, 0x4b000001, v134
	v_max_f32_e32 v135, 0x4b000001, v135
	v_perm_b32 v134, v135, v134, s46
	v_pk_fma_f32 v[156:157], v[156:157], s[62:63], v[128:129] op_sel_hi:[1,0,0]
	v_pk_fma_f32 v[158:159], v[158:159], s[62:63], v[128:129] op_sel_hi:[1,0,0]
	v_perm_b32 v134, v134, v144, s47
	v_max_f32_e32 v135, 0x4b000001, v158
	v_max_f32_e32 v144, 0x4b000001, v159
	v_max_f32_e32 v151, 0x4b000001, v156
	v_max_f32_e32 v153, 0x4b000001, v157
	v_perm_b32 v135, v144, v135, s46
	v_perm_b32 v144, v153, v151, s46
	v_perm_b32 v135, v144, v135, s47
	global_store_dwordx4 v[130:131], v[132:135], off offset:2048 nt
	v_pk_mul_f32 v[156:157], v[8:9], s[60:61] op_sel_hi:[1,0]
	v_pk_mul_f32 v[158:159], v[0:1], s[60:61] op_sel_hi:[1,0]
	v_pk_mul_f32 v[132:133], v[14:15], s[60:61] op_sel_hi:[1,0]
	v_pk_mul_f32 v[134:135], v[12:13], s[60:61] op_sel_hi:[1,0]
	v_exp_f32_e32 v132, v132
	v_exp_f32_e32 v134, v134
	v_exp_f32_e32 v135, v135
	v_exp_f32_e32 v133, v133
	v_exp_f32_e32 v156, v156
	v_exp_f32_e32 v157, v157
	v_pk_add_f32 v[134:135], v[134:135], 1.0 op_sel_hi:[1,0]
	v_pk_add_f32 v[132:133], v[132:133], 1.0 op_sel_hi:[1,0]
	v_rcp_f32_e32 v134, v134
	v_rcp_f32_e32 v135, v135
	v_rcp_f32_e32 v132, v132
	v_rcp_f32_e32 v133, v133
	v_pk_add_f32 v[156:157], v[156:157], 1.0 op_sel_hi:[1,0]
	v_pk_fma_f32 v[134:135], v[134:135], s[62:63], v[128:129] op_sel_hi:[1,0,0]
	v_rcp_f32_e32 v156, v156
	v_pk_fma_f32 v[132:133], v[132:133], s[62:63], v[128:129] op_sel_hi:[1,0,0]
	v_max_f32_e32 v134, 0x4b000001, v134
	v_max_f32_e32 v135, 0x4b000001, v135
	v_max_f32_e32 v132, 0x4b000001, v132
	v_max_f32_e32 v133, 0x4b000001, v133
	v_perm_b32 v134, v135, v134, s46
	v_perm_b32 v132, v133, v132, s46
	v_rcp_f32_e32 v157, v157
	v_perm_b32 v132, v132, v134, s47
	v_pk_mul_f32 v[134:135], v[10:11], s[60:61] op_sel_hi:[1,0]
	v_exp_f32_e32 v158, v158
	v_exp_f32_e32 v134, v134
	v_exp_f32_e32 v135, v135
	v_pk_fma_f32 v[156:157], v[156:157], s[62:63], v[128:129] op_sel_hi:[1,0,0]
	v_exp_f32_e32 v159, v159
	v_max_f32_e32 v133, 0x4b000001, v156
	v_max_f32_e32 v144, 0x4b000001, v157
	v_pk_mul_f32 v[156:157], v[4:5], s[60:61] op_sel_hi:[1,0]
	v_pk_add_f32 v[134:135], v[134:135], 1.0 op_sel_hi:[1,0]
	v_exp_f32_e32 v156, v156
	v_exp_f32_e32 v157, v157
	v_rcp_f32_e32 v134, v134
	v_rcp_f32_e32 v135, v135
	v_perm_b32 v133, v144, v133, s46
	v_pk_add_f32 v[156:157], v[156:157], 1.0 op_sel_hi:[1,0]
	v_pk_add_f32 v[158:159], v[158:159], 1.0 op_sel_hi:[1,0]
	v_pk_fma_f32 v[134:135], v[134:135], s[62:63], v[128:129] op_sel_hi:[1,0,0]
	v_rcp_f32_e32 v156, v156
	v_rcp_f32_e32 v157, v157
	v_max_f32_e32 v134, 0x4b000001, v134
	v_max_f32_e32 v135, 0x4b000001, v135
	v_perm_b32 v134, v135, v134, s46
	v_perm_b32 v133, v134, v133, s47
	v_pk_mul_f32 v[134:135], v[6:7], s[60:61] op_sel_hi:[1,0]
	v_pk_fma_f32 v[156:157], v[156:157], s[62:63], v[128:129] op_sel_hi:[1,0,0]
	v_exp_f32_e32 v134, v134
	v_exp_f32_e32 v135, v135
	v_max_f32_e32 v144, 0x4b000001, v156
	v_max_f32_e32 v151, 0x4b000001, v157
	v_pk_mul_f32 v[156:157], v[2:3], s[60:61] op_sel_hi:[1,0]
	v_pk_add_f32 v[134:135], v[134:135], 1.0 op_sel_hi:[1,0]
	v_exp_f32_e32 v156, v156
	v_exp_f32_e32 v157, v157
	v_rcp_f32_e32 v134, v134
	v_rcp_f32_e32 v135, v135
	v_rcp_f32_e32 v158, v158
	v_pk_add_f32 v[156:157], v[156:157], 1.0 op_sel_hi:[1,0]
	v_rcp_f32_e32 v159, v159
	v_rcp_f32_e32 v156, v156
	v_rcp_f32_e32 v157, v157
	v_pk_fma_f32 v[134:135], v[134:135], s[62:63], v[128:129] op_sel_hi:[1,0,0]
	v_perm_b32 v144, v151, v144, s46
	v_max_f32_e32 v134, 0x4b000001, v134
	v_max_f32_e32 v135, 0x4b000001, v135
	v_perm_b32 v134, v135, v134, s46
	v_pk_fma_f32 v[156:157], v[156:157], s[62:63], v[128:129] op_sel_hi:[1,0,0]
	v_pk_fma_f32 v[128:129], v[158:159], s[62:63], v[128:129] op_sel_hi:[1,0,0]
	v_perm_b32 v134, v134, v144, s47
	v_max_f32_e32 v128, 0x4b000001, v128
	v_max_f32_e32 v129, 0x4b000001, v129
	v_max_f32_e32 v135, 0x4b000001, v156
	v_max_f32_e32 v144, 0x4b000001, v157
	v_perm_b32 v128, v129, v128, s46
	v_perm_b32 v129, v144, v135, s46
	v_perm_b32 v135, v129, v128, s47
	global_store_dwordx4 v[130:131], v[132:135], off offset:3072 nt
	s_waitcnt vmcnt(8)

.LBB0_839:
	s_waitcnt lgkmcnt(14)
	v_sub_u32_e32 v0, s66, v3
	v_lshlrev_b32_e32 v0, 8, v0
	v_add_u32_e32 v0, s10, v0
	v_cmp_ge_i32_e32 vcc, v0, v2
	s_cbranch_vccnz .LBB0_823
	v_mov_b32_e32 v151, 0
	s_mov_b32 s8, 0
	v_mov_b32_e32 v0, 0
	v_mov_b32_e32 v1, v151
	v_mov_b32_e32 v2, v151
	v_mov_b32_e32 v3, v151
	v_mov_b32_e32 v4, v151
	v_mov_b32_e32 v5, v151
	v_mov_b32_e32 v6, v151
	v_mov_b32_e32 v7, v151
	v_mov_b32_e32 v8, v151
	v_mov_b32_e32 v9, v151
	v_mov_b32_e32 v10, v151
	v_mov_b32_e32 v11, v151
	v_mov_b32_e32 v12, v151
	v_mov_b32_e32 v13, v151
	v_mov_b32_e32 v14, v151
	v_mov_b32_e32 v15, v151
	v_mov_b32_e32 v16, 0
	v_mov_b32_e32 v17, v151
	v_mov_b32_e32 v18, v151
	v_mov_b32_e32 v19, v151
	v_mov_b32_e32 v20, v151
	v_mov_b32_e32 v21, v151
	v_mov_b32_e32 v22, v151
	v_mov_b32_e32 v23, v151
	v_mov_b32_e32 v24, v151
	v_mov_b32_e32 v25, v151
	v_mov_b32_e32 v26, v151
	v_mov_b32_e32 v27, v151
	v_mov_b32_e32 v28, v151
	v_mov_b32_e32 v29, v151
	v_mov_b32_e32 v30, v151
	v_mov_b32_e32 v31, v151
	v_mov_b32_e32 v32, 0
	v_mov_b32_e32 v33, v151
	v_mov_b32_e32 v34, v151
	v_mov_b32_e32 v35, v151
	v_mov_b32_e32 v36, v151
	v_mov_b32_e32 v37, v151
	v_mov_b32_e32 v38, v151
	v_mov_b32_e32 v39, v151
	v_mov_b32_e32 v40, v151
	v_mov_b32_e32 v41, v151
	v_mov_b32_e32 v42, v151
	v_mov_b32_e32 v43, v151
	v_mov_b32_e32 v44, v151
	v_mov_b32_e32 v45, v151
	v_mov_b32_e32 v46, v151
	v_mov_b32_e32 v47, v151
	v_mov_b32_e32 v48, 0
	v_mov_b32_e32 v49, v151
	v_mov_b32_e32 v50, v151
	v_mov_b32_e32 v51, v151
	v_mov_b32_e32 v52, v151
	v_mov_b32_e32 v53, v151
	v_mov_b32_e32 v54, v151
	v_mov_b32_e32 v55, v151
	v_mov_b32_e32 v56, v151
	v_mov_b32_e32 v57, v151
	v_mov_b32_e32 v58, v151
	v_mov_b32_e32 v59, v151
	v_mov_b32_e32 v60, v151
	v_mov_b32_e32 v61, v151
	v_mov_b32_e32 v62, v151
	v_mov_b32_e32 v63, v151
	v_mov_b32_e32 v155, v200
	v_mov_b32_e32 v159, v199
	v_mov_b32_e32 v163, v198
	v_mov_b32_e32 v167, v197
	v_mov_b32_e32 v171, v196
	v_mov_b32_e32 v175, v195
	v_mov_b32_e32 v176, v194
	v_mov_b32_e32 v185, v193
	v_add_u32_e32 v241, 0x10000, v192
	ds_read_b128 v[224:227], v155
	ds_read_b128 v[228:231], v159
	ds_read_b128 v[232:235], v163
	ds_read_b128 v[236:239], v167
.LBB0_841:
	s_waitcnt lgkmcnt(3)
	v_mfma_f32_32x32x16_bf16 v[64:79], v[224:227], v[112:115], 0
	ds_read_b128 v[224:227], v171
	s_waitcnt lgkmcnt(3)
	v_mfma_f32_32x32x16_bf16 v[64:79], v[228:231], v[116:119], v[64:79]
	ds_read_b128 v[228:231], v175
	s_waitcnt lgkmcnt(3)
	v_mfma_f32_32x32x16_bf16 v[64:79], v[232:235], v[120:123], v[64:79]
	ds_read_b128 v[232:235], v176
	s_waitcnt lgkmcnt(3)
	v_mfma_f32_32x32x16_bf16 v[64:79], v[236:239], v[124:127], v[64:79]
	ds_read_b128 v[236:239], v185
	ds_read_b64_tr_b16 v[208:209], v241
	ds_read_b64_tr_b16 v[210:211], v241 offset:2048
	s_waitcnt lgkmcnt(5)
	v_mfma_f32_32x32x16_bf16 v[64:79], v[224:227], v[128:131], v[64:79]
	ds_read_b64_tr_b16 v[212:213], v241 offset:256
	ds_read_b64_tr_b16 v[214:215], v241 offset:2304
	s_waitcnt lgkmcnt(6)
	v_mfma_f32_32x32x16_bf16 v[64:79], v[228:231], v[132:135], v[64:79]
	ds_read_b64_tr_b16 v[216:217], v241 offset:512
	ds_read_b64_tr_b16 v[218:219], v241 offset:2560
	s_waitcnt lgkmcnt(7)
	v_mfma_f32_32x32x16_bf16 v[64:79], v[232:235], v[136:139], v[64:79]
	ds_read_b64_tr_b16 v[220:221], v241 offset:768
	ds_read_b64_tr_b16 v[222:223], v241 offset:2816
	s_waitcnt lgkmcnt(8)
	v_mfma_f32_32x32x16_bf16 v[64:79], v[236:239], v[140:143], v[64:79]
	v_add_u32_e32 v155, 0x2000, v155
	v_add_u32_e32 v159, 0x2000, v159
	v_add_u32_e32 v163, 0x2000, v163
	v_add_u32_e32 v167, 0x2000, v167
	v_add_u32_e32 v171, 0x2000, v171
	v_add_u32_e32 v175, 0x2000, v175
	v_add_u32_e32 v176, 0x2000, v176
	v_add_u32_e32 v185, 0x2000, v185
	s_nop 3
	v_exp_f32_e32 v224, v64
	v_exp_f32_e32 v225, v65
	v_exp_f32_e32 v226, v66
	v_exp_f32_e32 v227, v67
	v_exp_f32_e32 v228, v68
	v_exp_f32_e32 v229, v69
	v_exp_f32_e32 v230, v70
	v_exp_f32_e32 v231, v71
	v_exp_f32_e32 v232, v72
	v_exp_f32_e32 v233, v73
	v_exp_f32_e32 v234, v74
	v_exp_f32_e32 v235, v75
	v_exp_f32_e32 v236, v76
	v_exp_f32_e32 v237, v77
	v_exp_f32_e32 v238, v78
	v_exp_f32_e32 v239, v79
	v_cvt_pk_bf16_f32 v64, v224, v225
	v_cvt_pk_bf16_f32 v65, v226, v227
	v_cvt_pk_bf16_f32 v66, v228, v229
	v_cvt_pk_bf16_f32 v67, v230, v231
	v_cvt_pk_bf16_f32 v68, v232, v233
	v_cvt_pk_bf16_f32 v69, v234, v235
	v_cvt_pk_bf16_f32 v70, v236, v237
	v_cvt_pk_bf16_f32 v71, v238, v239
	s_waitcnt lgkmcnt(6)
	v_mfma_f32_32x32x16_bf16 v[48:63], v[208:211], v[64:67], v[48:63]
	ds_read_b64_tr_b16 v[208:209], v241 offset:4096
	ds_read_b64_tr_b16 v[210:211], v241 offset:6144
	v_add_f32_e32 v240, 0, v224
	v_add_f32_e32 v240, v225, v240
	v_add_f32_e32 v240, v226, v240
	v_add_f32_e32 v240, v227, v240
	v_add_f32_e32 v240, v228, v240
	s_waitcnt lgkmcnt(6)
	v_mfma_f32_32x32x16_bf16 v[32:47], v[212:215], v[64:67], v[32:47]
	ds_read_b64_tr_b16 v[212:213], v241 offset:4352
	ds_read_b64_tr_b16 v[214:215], v241 offset:6400
	v_add_f32_e32 v240, v229, v240
	v_add_f32_e32 v240, v230, v240
	v_add_f32_e32 v240, v231, v240
	v_add_f32_e32 v240, v232, v240
	s_waitcnt lgkmcnt(6)
	v_mfma_f32_32x32x16_bf16 v[16:31], v[216:219], v[64:67], v[16:31]
	ds_read_b64_tr_b16 v[216:217], v241 offset:4608
	ds_read_b64_tr_b16 v[218:219], v241 offset:6656
	v_add_f32_e32 v240, v233, v240
	v_add_f32_e32 v240, v234, v240
	v_add_f32_e32 v240, v235, v240
	v_add_f32_e32 v240, v236, v240
	s_waitcnt lgkmcnt(6)
	v_mfma_f32_32x32x16_bf16 v[0:15], v[220:223], v[64:67], v[0:15]
	ds_read_b64_tr_b16 v[220:221], v241 offset:4864
	ds_read_b64_tr_b16 v[222:223], v241 offset:6912
	v_add_f32_e32 v240, v237, v240
	v_add_f32_e32 v240, v238, v240
	v_add_f32_e32 v240, v239, v240
	v_add_f32_e32 v151, v151, v240
	s_waitcnt lgkmcnt(6)
	v_mfma_f32_32x32x16_bf16 v[48:63], v[208:211], v[68:71], v[48:63]
	ds_read_b128 v[224:227], v155
	s_waitcnt lgkmcnt(5)
	v_mfma_f32_32x32x16_bf16 v[32:47], v[212:215], v[68:71], v[32:47]
	ds_read_b128 v[228:231], v159
	s_waitcnt lgkmcnt(4)
	v_mfma_f32_32x32x16_bf16 v[16:31], v[216:219], v[68:71], v[16:31]
	ds_read_b128 v[232:235], v163
	s_waitcnt lgkmcnt(3)
	v_mfma_f32_32x32x16_bf16 v[0:15], v[220:223], v[68:71], v[0:15]
	ds_read_b128 v[236:239], v167
	v_add_u32_e32 v241, 0x2000, v241
	s_addk_i32 s8, 0x2000
	s_cmp_lg_u32 s8, 0x10000
	s_cbranch_scc1 .LBB0_841
	s_waitcnt lgkmcnt(0)
	ds_bpermute_b32 v66, v191, v151
	v_lshrrev_b32_e32 v65, 2, v207
	v_cmp_ne_u32_e32 vcc, -1, v207
	v_and_b32_e32 v64, 3, v207
	v_lshl_add_u32 v65, s68, 13, v65
	v_mad_u64_u32 v[64:65], s[8:9], v65, 3, v[64:65]
	s_and_b64 s[30:31], vcc, s[4:5]
	s_and_saveexec_b64 s[8:9], s[30:31]
	s_cbranch_execz .LBB0_844
	v_ashrrev_i32_e32 v65, 31, v64
	s_waitcnt lgkmcnt(0)
	v_add_f32_e32 v68, v151, v66
	v_lshl_add_u64 v[66:67], v[64:65], 2, s[36:37]
	global_store_dword v[66:67], v68, off

	.amdhsa_kernel _Z6mk_fwdILi0EEv4Args
		.amdhsa_group_segment_fixed_size 0
		.amdhsa_private_segment_fixed_size 0
		.amdhsa_kernarg_size 456
		.amdhsa_user_sgpr_count 2
		.amdhsa_user_sgpr_dispatch_ptr 0
		.amdhsa_user_sgpr_queue_ptr 0
		.amdhsa_user_sgpr_kernarg_segment_ptr 1
		.amdhsa_user_sgpr_dispatch_id 0
		.amdhsa_user_sgpr_kernarg_preload_length 0
		.amdhsa_user_sgpr_kernarg_preload_offset 0
		.amdhsa_user_sgpr_private_segment_size 0
		.amdhsa_uses_dynamic_stack 0
		.amdhsa_enable_private_segment 0
		.amdhsa_system_sgpr_workgroup_id_x 1
		.amdhsa_system_sgpr_workgroup_id_y 0
		.amdhsa_system_sgpr_workgroup_id_z 0
		.amdhsa_system_sgpr_workgroup_info 0
		.amdhsa_system_vgpr_workitem_id 0
		.amdhsa_next_free_vgpr 256
		.amdhsa_next_free_sgpr 102
		.amdhsa_accum_offset 256
		.amdhsa_reserve_vcc 1
		.amdhsa_float_round_mode_32 0
		.amdhsa_float_round_mode_16_64 0
		.amdhsa_float_denorm_mode_32 3
		.amdhsa_float_denorm_mode_16_64 3
		.amdhsa_dx10_clamp 1
		.amdhsa_ieee_mode 1
		.amdhsa_fp16_overflow 0
		.amdhsa_tg_split 0
		.amdhsa_exception_fp_ieee_invalid_op 0
		.amdhsa_exception_fp_denorm_src 0
		.amdhsa_exception_fp_ieee_div_zero 0
		.amdhsa_exception_fp_ieee_overflow 0
		.amdhsa_exception_fp_ieee_underflow 0
		.amdhsa_exception_fp_ieee_inexact 0
		.amdhsa_exception_int_div_zero 0
	.end_amdhsa_kernel

amdhsa.kernels:
  - .agpr_count:     0
    .args:
      - .offset:         0
        .size:           200
        .value_kind:     by_value
      - .offset:         200
        .size:           4
        .value_kind:     hidden_block_count_x
      - .offset:         204
        .size:           4
        .value_kind:     hidden_block_count_y
      - .offset:         208
        .size:           4
        .value_kind:     hidden_block_count_z
      - .offset:         212
        .size:           2
        .value_kind:     hidden_group_size_x
      - .offset:         214
        .size:           2
        .value_kind:     hidden_group_size_y
      - .offset:         216
        .size:           2
        .value_kind:     hidden_group_size_z
      - .offset:         218
        .size:           2
        .value_kind:     hidden_remainder_x
      - .offset:         220
        .size:           2
        .value_kind:     hidden_remainder_y
      - .offset:         222
        .size:           2
        .value_kind:     hidden_remainder_z
      - .offset:         240
        .size:           8
        .value_kind:     hidden_global_offset_x
      - .offset:         248
        .size:           8
        .value_kind:     hidden_global_offset_y
      - .offset:         256
        .size:           8
        .value_kind:     hidden_global_offset_z
      - .offset:         264
        .size:           2
        .value_kind:     hidden_grid_dims
      - .offset:         320
        .size:           4
        .value_kind:     hidden_dynamic_lds_size
    .group_segment_fixed_size: 0
    .kernarg_segment_align: 8
    .kernarg_segment_size: 456
    .language:       OpenCL C
    .language_version:
      - 2
      - 0
    .max_flat_workgroup_size: 512
    .name:           _Z6mk_fwdILi0EEv4Args
    .private_segment_fixed_size: 0
    .sgpr_count:     108
    .sgpr_spill_count: 12
    .symbol:         _Z6mk_fwdILi0EEv4Args.kd
    .uniform_work_group_size: 1
    .uses_dynamic_stack: false
    .vgpr_count:     256
    .vgpr_spill_count: 0
    .wavefront_size: 64
